# fast loop: the two halves of the workgroup issue their K/V LDS-DMA pieces at different points (comp 0 at the rendezvous, comp 1 at the end of the sub-tile) instead of all 8 waves at once
# speedup vs baseline: 1.0040x; 1.0015x over previous
.Lat_fbackb:
	v_exp_f32_e32 v96, v96
	v_exp_f32_e32 v97, v97
	v_exp_f32_e32 v98, v98
	v_exp_f32_e32 v99, v99
	v_exp_f32_e32 v100, v100
	v_exp_f32_e32 v101, v101
	v_exp_f32_e32 v102, v102
	v_exp_f32_e32 v103, v103
	v_cvt_pk_bf16_f32 v162, v96, v97
	v_cvt_pk_bf16_f32 v163, v98, v99
	v_cvt_pk_bf16_f32 v164, v100, v101
	v_cvt_pk_bf16_f32 v165, v102, v103
	v_pk_add_f32 v[130:131], v[130:131], v[96:97]
	v_pk_add_f32 v[130:131], v[130:131], v[98:99]
	v_pk_add_f32 v[130:131], v[130:131], v[100:101]
	v_pk_add_f32 v[130:131], v[130:131], v[102:103]
	v_mfma_f32_32x32x16_bf16 v[80:95], v[162:165], v[168:171], v[80:95]
	v_exp_f32_e32 v104, v104
	v_exp_f32_e32 v105, v105
	v_exp_f32_e32 v106, v106
	v_exp_f32_e32 v107, v107
	v_mfma_f32_32x32x16_bf16 v[200:215], v[162:165], v[172:175], v[200:215]
	v_exp_f32_e32 v108, v108
	v_exp_f32_e32 v109, v109
	v_exp_f32_e32 v110, v110
	v_exp_f32_e32 v111, v111
	v_cvt_pk_bf16_f32 v162, v104, v105
	v_cvt_pk_bf16_f32 v163, v106, v107
	v_cvt_pk_bf16_f32 v164, v108, v109
	v_cvt_pk_bf16_f32 v165, v110, v111
	v_pk_add_f32 v[130:131], v[130:131], v[104:105]
	v_pk_add_f32 v[130:131], v[130:131], v[106:107]
	v_pk_add_f32 v[130:131], v[130:131], v[108:109]
	v_pk_add_f32 v[130:131], v[130:131], v[110:111]
	v_mfma_f32_32x32x16_bf16 v[80:95], v[162:165], v[176:179], v[80:95]
	v_exp_f32_e32 v112, v112
	v_exp_f32_e32 v113, v113
	v_exp_f32_e32 v114, v114
	v_exp_f32_e32 v115, v115
	v_mfma_f32_32x32x16_bf16 v[200:215], v[162:165], v[180:183], v[200:215]
	v_exp_f32_e32 v116, v116
	v_exp_f32_e32 v117, v117
	v_exp_f32_e32 v118, v118
	v_exp_f32_e32 v119, v119
	v_cvt_pk_bf16_f32 v162, v112, v113
	v_cvt_pk_bf16_f32 v163, v114, v115
	v_cvt_pk_bf16_f32 v164, v116, v117
	v_cvt_pk_bf16_f32 v165, v118, v119
	v_pk_add_f32 v[130:131], v[130:131], v[112:113]
	v_pk_add_f32 v[130:131], v[130:131], v[114:115]
	v_pk_add_f32 v[130:131], v[130:131], v[116:117]
	v_pk_add_f32 v[130:131], v[130:131], v[118:119]
	v_mfma_f32_32x32x16_bf16 v[80:95], v[162:165], v[184:187], v[80:95]
	v_exp_f32_e32 v120, v120
	v_exp_f32_e32 v121, v121
	v_exp_f32_e32 v122, v122
	v_exp_f32_e32 v123, v123
	v_mfma_f32_32x32x16_bf16 v[200:215], v[162:165], v[188:191], v[200:215]
	v_exp_f32_e32 v124, v124
	v_exp_f32_e32 v125, v125
	v_exp_f32_e32 v126, v126
	v_exp_f32_e32 v127, v127
	v_cvt_pk_bf16_f32 v162, v120, v121
	v_cvt_pk_bf16_f32 v163, v122, v123
	v_cvt_pk_bf16_f32 v164, v124, v125
	v_cvt_pk_bf16_f32 v165, v126, v127
	v_pk_add_f32 v[130:131], v[130:131], v[120:121]
	v_pk_add_f32 v[130:131], v[130:131], v[122:123]
	v_pk_add_f32 v[130:131], v[130:131], v[124:125]
	v_pk_add_f32 v[130:131], v[130:131], v[126:127]
	v_mfma_f32_32x32x16_bf16 v[80:95], v[162:165], v[192:195], v[80:95]
	v_mfma_f32_32x32x16_bf16 v[200:215], v[162:165], v[196:199], v[200:215]
	s_waitcnt lgkmcnt(0)
	v_mfma_f32_32x32x16_bf16 v[96:111], v[48:51], v[136:139], v[32:47]
	ds_read_b64_tr_b16 v[168:169], v146 offset:8192
	ds_read_b64_tr_b16 v[170:171], v146 offset:9216
	ds_read_b64_tr_b16 v[172:173], v146 offset:8704
	ds_read_b64_tr_b16 v[174:175], v146 offset:9728
	v_mfma_f32_32x32x16_bf16 v[96:111], v[52:55], v[140:143], v[96:111]
	ds_read_b64_tr_b16 v[176:177], v146 offset:10240
	ds_read_b64_tr_b16 v[178:179], v146 offset:11264
	ds_read_b64_tr_b16 v[180:181], v146 offset:10752
	ds_read_b64_tr_b16 v[182:183], v146 offset:11776
	v_mfma_f32_32x32x16_bf16 v[112:127], v[56:59], v[136:139], v[32:47]
	ds_read_b64_tr_b16 v[184:185], v146 offset:12288
	ds_read_b64_tr_b16 v[186:187], v146 offset:13312
	ds_read_b64_tr_b16 v[188:189], v146 offset:12800
	ds_read_b64_tr_b16 v[190:191], v146 offset:13824
	v_mfma_f32_32x32x16_bf16 v[112:127], v[60:63], v[140:143], v[112:127]
	ds_read_b64_tr_b16 v[192:193], v146 offset:14336
	ds_read_b64_tr_b16 v[194:195], v146 offset:15360
	ds_read_b64_tr_b16 v[196:197], v146 offset:14848
	ds_read_b64_tr_b16 v[198:199], v146 offset:15872
	v_exp_f32_e32 v96, v96
	v_exp_f32_e32 v97, v97
	v_exp_f32_e32 v98, v98
	v_exp_f32_e32 v99, v99
	v_exp_f32_e32 v100, v100
	v_exp_f32_e32 v101, v101
	v_exp_f32_e32 v102, v102
	v_exp_f32_e32 v103, v103
	v_cvt_pk_bf16_f32 v162, v96, v97
	v_cvt_pk_bf16_f32 v163, v98, v99
	v_cvt_pk_bf16_f32 v164, v100, v101
	v_cvt_pk_bf16_f32 v165, v102, v103
	v_pk_add_f32 v[128:129], v[128:129], v[96:97]
	v_pk_add_f32 v[128:129], v[128:129], v[98:99]
	v_pk_add_f32 v[128:129], v[128:129], v[100:101]
	v_pk_add_f32 v[128:129], v[128:129], v[102:103]
	s_waitcnt lgkmcnt(12)
	v_mfma_f32_32x32x16_bf16 v[0:15], v[162:165], v[168:171], v[0:15]
	v_exp_f32_e32 v104, v104
	v_exp_f32_e32 v105, v105
	v_exp_f32_e32 v106, v106
	v_exp_f32_e32 v107, v107
	v_mfma_f32_32x32x16_bf16 v[16:31], v[162:165], v[172:175], v[16:31]
	v_exp_f32_e32 v108, v108
	v_exp_f32_e32 v109, v109
	v_exp_f32_e32 v110, v110
	v_exp_f32_e32 v111, v111
	v_cvt_pk_bf16_f32 v162, v104, v105
	v_cvt_pk_bf16_f32 v163, v106, v107
	v_cvt_pk_bf16_f32 v164, v108, v109
	v_cvt_pk_bf16_f32 v165, v110, v111
	v_pk_add_f32 v[128:129], v[128:129], v[104:105]
	v_pk_add_f32 v[128:129], v[128:129], v[106:107]
	v_pk_add_f32 v[128:129], v[128:129], v[108:109]
	v_pk_add_f32 v[128:129], v[128:129], v[110:111]
	s_waitcnt lgkmcnt(8)
	v_mfma_f32_32x32x16_bf16 v[0:15], v[162:165], v[176:179], v[0:15]
	v_exp_f32_e32 v112, v112
	v_exp_f32_e32 v113, v113
	v_exp_f32_e32 v114, v114
	v_exp_f32_e32 v115, v115
	v_mfma_f32_32x32x16_bf16 v[16:31], v[162:165], v[180:183], v[16:31]
	v_mfma_f32_32x32x16_bf16 v[96:111], v[48:51], v[150:153], v[64:79]
	v_exp_f32_e32 v116, v116
	v_exp_f32_e32 v117, v117
	v_exp_f32_e32 v118, v118
	v_exp_f32_e32 v119, v119
	v_mfma_f32_32x32x16_bf16 v[96:111], v[52:55], v[154:157], v[96:111]
	v_cvt_pk_bf16_f32 v162, v112, v113
	v_cvt_pk_bf16_f32 v163, v114, v115
	v_cvt_pk_bf16_f32 v164, v116, v117
	v_cvt_pk_bf16_f32 v165, v118, v119
	v_pk_add_f32 v[128:129], v[128:129], v[112:113]
	v_pk_add_f32 v[128:129], v[128:129], v[114:115]
	v_pk_add_f32 v[128:129], v[128:129], v[116:117]
	v_pk_add_f32 v[128:129], v[128:129], v[118:119]
	s_waitcnt lgkmcnt(4)
; #define AT_LOAD(K0, K1, V0, V1, T) do { const size_t e_ = (size_t)(128 * (T) + sr) * 64 + sc; \
;         K0 = *(const bf16x8*)(kcp + e_); V0 = *(const bf16x8*)(vcp + e_); K1 = *(const bf16x8*)(kcp + e_ + 64 * 64); V1 = *(const bf16x8*)(vcp + e_ + 64 * 64); } while (0)
; #define AT_STORE(K0, K1, V0, V1, BUF) do { *(LAS bf16x8*)(lds + AT_K + (BUF) * AT_KB + kst0) = K0; *(LAS bf16x8*)(lds + AT_K + (BUF) * AT_KB + kst1) = K1; \
;         *(LAS bf16x8*)(lds + AT_V + (BUF) * AT_VB + vst0) = V0; *(LAS bf16x8*)(lds + AT_V + (BUF) * AT_VB + vst1) = V1; } while (0)
; template <int VAR>
; __device__ __forceinline__ void attn_unit(const Args& a, int l, int b, int h, int qrow0  , bool ctxu, const bf16* Z, bf16* Y, LAS unsigned char* lds) {
;     ...
;     for (int t = 0; t < NT; t += 2) {
;         __syncthreads();
;         if (t + 2 < NT) AT_LOAD(ka0, ka1, va0, va1, t + 2);
;         attn_tile(Kb0, vb0, q0, q1, negm, m, o0, o1, lacc, t == 0, wsf, r32, hi);
;         AT_STORE(kb0, kb1, vb0_, vb1_, 1);
;         __syncthreads();
;         if (t + 3 < NT) AT_LOAD(kb0, kb1, vb0_, vb1_, t + 3);
;         attn_tile(Kb0 + AT_KB, vb0 + AT_VB, q0, q1, negm, m, o0, o1, lacc, false, wsf, r32, hi);
;         if (t + 2 < NT) AT_STORE(ka0, ka1, va0, va1, 0);
	v_mfma_f32_32x32x16_bf16 v[0:15], v[162:165], v[184:187], v[0:15]
	v_exp_f32_e32 v120, v120
	v_exp_f32_e32 v121, v121
	v_exp_f32_e32 v122, v122
	v_exp_f32_e32 v123, v123
	v_mfma_f32_32x32x16_bf16 v[16:31], v[162:165], v[188:191], v[16:31]
	v_exp_f32_e32 v124, v124
	v_exp_f32_e32 v125, v125
	v_exp_f32_e32 v126, v126
	v_exp_f32_e32 v127, v127
	v_cvt_pk_bf16_f32 v162, v120, v121
	v_cvt_pk_bf16_f32 v163, v122, v123
	v_cvt_pk_bf16_f32 v164, v124, v125
	v_cvt_pk_bf16_f32 v165, v126, v127
	v_pk_add_f32 v[128:129], v[128:129], v[120:121]
	v_pk_add_f32 v[128:129], v[128:129], v[122:123]
	v_pk_add_f32 v[128:129], v[128:129], v[124:125]
	v_pk_add_f32 v[128:129], v[128:129], v[126:127]
	v_mfma_f32_32x32x16_bf16 v[112:127], v[56:59], v[150:153], v[64:79]
	v_mfma_f32_32x32x16_bf16 v[112:127], v[60:63], v[154:157], v[112:127]
	s_waitcnt lgkmcnt(0)
	v_mfma_f32_32x32x16_bf16 v[0:15], v[162:165], v[192:195], v[0:15]
	v_mfma_f32_32x32x16_bf16 v[16:31], v[162:165], v[196:199], v[16:31]
	v_exp_f32_e32 v96, v96
	v_exp_f32_e32 v97, v97
	v_exp_f32_e32 v98, v98
	v_exp_f32_e32 v99, v99
	v_exp_f32_e32 v100, v100
	v_exp_f32_e32 v101, v101
	v_exp_f32_e32 v102, v102
	v_exp_f32_e32 v103, v103
	v_cvt_pk_bf16_f32 v162, v96, v97
	v_cvt_pk_bf16_f32 v163, v98, v99
	v_cvt_pk_bf16_f32 v164, v100, v101
	v_cvt_pk_bf16_f32 v165, v102, v103
	v_pk_add_f32 v[130:131], v[130:131], v[96:97]
	v_pk_add_f32 v[130:131], v[130:131], v[98:99]
	v_pk_add_f32 v[130:131], v[130:131], v[100:101]
	v_pk_add_f32 v[130:131], v[130:131], v[102:103]
	v_mfma_f32_32x32x16_bf16 v[80:95], v[162:165], v[168:171], v[80:95]
	v_exp_f32_e32 v104, v104
	v_exp_f32_e32 v105, v105
	v_exp_f32_e32 v106, v106
	v_exp_f32_e32 v107, v107
	v_mfma_f32_32x32x16_bf16 v[200:215], v[162:165], v[172:175], v[200:215]
	v_exp_f32_e32 v108, v108
	v_exp_f32_e32 v109, v109
	v_exp_f32_e32 v110, v110
	v_exp_f32_e32 v111, v111
	v_cvt_pk_bf16_f32 v162, v104, v105
	v_cvt_pk_bf16_f32 v163, v106, v107
	v_cvt_pk_bf16_f32 v164, v108, v109
	v_cvt_pk_bf16_f32 v165, v110, v111
	v_pk_add_f32 v[130:131], v[130:131], v[104:105]
	v_pk_add_f32 v[130:131], v[130:131], v[106:107]
	v_pk_add_f32 v[130:131], v[130:131], v[108:109]
	v_pk_add_f32 v[130:131], v[130:131], v[110:111]
	v_mfma_f32_32x32x16_bf16 v[80:95], v[162:165], v[176:179], v[80:95]
	v_exp_f32_e32 v112, v112
	v_exp_f32_e32 v113, v113
	v_exp_f32_e32 v114, v114
	v_exp_f32_e32 v115, v115
	v_mfma_f32_32x32x16_bf16 v[200:215], v[162:165], v[180:183], v[200:215]
	v_exp_f32_e32 v116, v116
	v_exp_f32_e32 v117, v117
	v_exp_f32_e32 v118, v118
	v_exp_f32_e32 v119, v119
	v_cvt_pk_bf16_f32 v162, v112, v113
	v_cvt_pk_bf16_f32 v163, v114, v115
	v_cvt_pk_bf16_f32 v164, v116, v117
	v_cvt_pk_bf16_f32 v165, v118, v119
	v_pk_add_f32 v[130:131], v[130:131], v[112:113]
	v_pk_add_f32 v[130:131], v[130:131], v[114:115]
	v_pk_add_f32 v[130:131], v[130:131], v[116:117]
	v_pk_add_f32 v[130:131], v[130:131], v[118:119]
	v_mfma_f32_32x32x16_bf16 v[80:95], v[162:165], v[184:187], v[80:95]
	v_exp_f32_e32 v120, v120
	v_exp_f32_e32 v121, v121
	v_exp_f32_e32 v122, v122
	v_exp_f32_e32 v123, v123
	v_mfma_f32_32x32x16_bf16 v[200:215], v[162:165], v[188:191], v[200:215]
	v_exp_f32_e32 v124, v124
	v_exp_f32_e32 v125, v125
	v_exp_f32_e32 v126, v126
	v_exp_f32_e32 v127, v127
	v_cvt_pk_bf16_f32 v162, v120, v121
	v_cvt_pk_bf16_f32 v163, v122, v123
	v_cvt_pk_bf16_f32 v164, v124, v125
	v_cvt_pk_bf16_f32 v165, v126, v127
	v_pk_add_f32 v[130:131], v[130:131], v[120:121]
	v_pk_add_f32 v[130:131], v[130:131], v[122:123]
	v_pk_add_f32 v[130:131], v[130:131], v[124:125]
	v_pk_add_f32 v[130:131], v[130:131], v[126:127]
	s_waitcnt vmcnt(4)
	s_waitcnt lgkmcnt(0)
	s_barrier
	s_cmp_eq_u32 s33, 21
	s_cbranch_scc1 .Lat_ndF1
	s_cmp_eq_u32 s8, 0
	s_cbranch_scc0 .Lat_ndF1
	s_add_u32 m0, s51, 0x0
	s_nop 0
	global_load_lds_dwordx4 v158, s[36:37]
	s_add_u32 m0, s51, 0x2000
	s_nop 0
	global_load_lds_dwordx4 v159, s[36:37]
	s_add_u32 m0, s51, 0xc000
	s_nop 0
	global_load_lds_dwordx4 v160, s[48:49]
	s_add_u32 m0, s51, 0xe000
	s_nop 0
	global_load_lds_dwordx4 v161, s[48:49]
	s_add_u32 s36, s36, 0x4000
	s_addc_u32 s37, s37, 0
	s_add_u32 s48, s48, 0x4000
	s_addc_u32 s49, s49, 0
.Lat_ndF1:
	ds_read_b128 v[48:51], v144 offset:16384
	ds_read_b128 v[52:55], v145 offset:16384
	ds_read_b128 v[56:59], v144 offset:20480
	ds_read_b128 v[60:63], v145 offset:20480
	v_mfma_f32_32x32x16_bf16 v[80:95], v[162:165], v[192:195], v[80:95]
	v_mfma_f32_32x32x16_bf16 v[200:215], v[162:165], v[196:199], v[200:215]
	s_cmp_eq_u32 s33, 21
	s_cbranch_scc1 .Lat_nlF1
	s_cmp_eq_u32 s8, 1
	s_cbranch_scc0 .Lat_nlF1
	s_add_u32 m0, s51, 0x0
	s_nop 0
	global_load_lds_dwordx4 v158, s[36:37]
	s_add_u32 m0, s51, 0x2000
	s_nop 0
	global_load_lds_dwordx4 v159, s[36:37]
	s_add_u32 m0, s51, 0xc000
	s_nop 0
	global_load_lds_dwordx4 v160, s[48:49]
	s_add_u32 m0, s51, 0xe000
	s_nop 0
	global_load_lds_dwordx4 v161, s[48:49]
	s_add_u32 s36, s36, 0x4000
	s_addc_u32 s37, s37, 0
	s_add_u32 s48, s48, 0x4000
	s_addc_u32 s49, s49, 0
.Lat_nlF1:
	s_waitcnt lgkmcnt(0)
	v_mfma_f32_32x32x16_bf16 v[96:111], v[48:51], v[136:139], v[32:47]
	ds_read_b64_tr_b16 v[168:169], v146 offset:16384
	ds_read_b64_tr_b16 v[170:171], v146 offset:17408
	ds_read_b64_tr_b16 v[172:173], v146 offset:16896
	ds_read_b64_tr_b16 v[174:175], v146 offset:17920
	v_mfma_f32_32x32x16_bf16 v[96:111], v[52:55], v[140:143], v[96:111]
	ds_read_b64_tr_b16 v[176:177], v146 offset:18432
	ds_read_b64_tr_b16 v[178:179], v146 offset:19456
	ds_read_b64_tr_b16 v[180:181], v146 offset:18944
	ds_read_b64_tr_b16 v[182:183], v146 offset:19968
	v_mfma_f32_32x32x16_bf16 v[112:127], v[56:59], v[136:139], v[32:47]
	ds_read_b64_tr_b16 v[184:185], v146 offset:20480
	ds_read_b64_tr_b16 v[186:187], v146 offset:21504
	ds_read_b64_tr_b16 v[188:189], v146 offset:20992
	ds_read_b64_tr_b16 v[190:191], v146 offset:22016
	v_mfma_f32_32x32x16_bf16 v[112:127], v[60:63], v[140:143], v[112:127]
	ds_read_b64_tr_b16 v[192:193], v146 offset:22528
	ds_read_b64_tr_b16 v[194:195], v146 offset:23552
	ds_read_b64_tr_b16 v[196:197], v146 offset:23040
	ds_read_b64_tr_b16 v[198:199], v146 offset:24064
	v_exp_f32_e32 v96, v96
	v_exp_f32_e32 v97, v97
	v_exp_f32_e32 v98, v98
	v_exp_f32_e32 v99, v99
	v_exp_f32_e32 v100, v100
	v_exp_f32_e32 v101, v101
	v_exp_f32_e32 v102, v102
	v_exp_f32_e32 v103, v103
	v_cvt_pk_bf16_f32 v162, v96, v97
	v_cvt_pk_bf16_f32 v163, v98, v99
	v_cvt_pk_bf16_f32 v164, v100, v101
	v_cvt_pk_bf16_f32 v165, v102, v103
	v_pk_add_f32 v[128:129], v[128:129], v[96:97]
	v_pk_add_f32 v[128:129], v[128:129], v[98:99]
	v_pk_add_f32 v[128:129], v[128:129], v[100:101]
	v_pk_add_f32 v[128:129], v[128:129], v[102:103]
	s_waitcnt lgkmcnt(12)
	v_mfma_f32_32x32x16_bf16 v[0:15], v[162:165], v[168:171], v[0:15]
	v_exp_f32_e32 v104, v104
	v_exp_f32_e32 v105, v105
	v_exp_f32_e32 v106, v106
	v_exp_f32_e32 v107, v107
	v_mfma_f32_32x32x16_bf16 v[16:31], v[162:165], v[172:175], v[16:31]
	v_exp_f32_e32 v108, v108
	v_exp_f32_e32 v109, v109
	v_exp_f32_e32 v110, v110
	v_exp_f32_e32 v111, v111
	v_cvt_pk_bf16_f32 v162, v104, v105
	v_cvt_pk_bf16_f32 v163, v106, v107
	v_cvt_pk_bf16_f32 v164, v108, v109
	v_cvt_pk_bf16_f32 v165, v110, v111
	v_pk_add_f32 v[128:129], v[128:129], v[104:105]
	v_pk_add_f32 v[128:129], v[128:129], v[106:107]
	v_pk_add_f32 v[128:129], v[128:129], v[108:109]
	v_pk_add_f32 v[128:129], v[128:129], v[110:111]
	s_waitcnt lgkmcnt(8)
	v_mfma_f32_32x32x16_bf16 v[0:15], v[162:165], v[176:179], v[0:15]
	v_exp_f32_e32 v112, v112
	v_exp_f32_e32 v113, v113
	v_exp_f32_e32 v114, v114
	v_exp_f32_e32 v115, v115
	v_mfma_f32_32x32x16_bf16 v[16:31], v[162:165], v[180:183], v[16:31]
	v_mfma_f32_32x32x16_bf16 v[96:111], v[48:51], v[150:153], v[64:79]
	v_exp_f32_e32 v116, v116
	v_exp_f32_e32 v117, v117
	v_exp_f32_e32 v118, v118
	v_exp_f32_e32 v119, v119
	v_mfma_f32_32x32x16_bf16 v[96:111], v[52:55], v[154:157], v[96:111]
	v_cvt_pk_bf16_f32 v162, v112, v113
	v_cvt_pk_bf16_f32 v163, v114, v115
	v_cvt_pk_bf16_f32 v164, v116, v117
	v_cvt_pk_bf16_f32 v165, v118, v119
	v_pk_add_f32 v[128:129], v[128:129], v[112:113]
	v_pk_add_f32 v[128:129], v[128:129], v[114:115]
	v_pk_add_f32 v[128:129], v[128:129], v[116:117]
	v_pk_add_f32 v[128:129], v[128:129], v[118:119]
	s_waitcnt lgkmcnt(4)
	v_mfma_f32_32x32x16_bf16 v[0:15], v[162:165], v[184:187], v[0:15]
	v_exp_f32_e32 v120, v120
	v_exp_f32_e32 v121, v121
	v_exp_f32_e32 v122, v122
	v_exp_f32_e32 v123, v123
	v_mfma_f32_32x32x16_bf16 v[16:31], v[162:165], v[188:191], v[16:31]
	v_exp_f32_e32 v124, v124
	v_exp_f32_e32 v125, v125
	v_exp_f32_e32 v126, v126
	v_exp_f32_e32 v127, v127
	v_cvt_pk_bf16_f32 v162, v120, v121
	v_cvt_pk_bf16_f32 v163, v122, v123
	v_cvt_pk_bf16_f32 v164, v124, v125
	v_cvt_pk_bf16_f32 v165, v126, v127
	v_pk_add_f32 v[128:129], v[128:129], v[120:121]
	v_pk_add_f32 v[128:129], v[128:129], v[122:123]
	v_pk_add_f32 v[128:129], v[128:129], v[124:125]
	v_pk_add_f32 v[128:129], v[128:129], v[126:127]
	v_mfma_f32_32x32x16_bf16 v[112:127], v[56:59], v[150:153], v[64:79]
	v_mfma_f32_32x32x16_bf16 v[112:127], v[60:63], v[154:157], v[112:127]
	s_waitcnt lgkmcnt(0)
	v_mfma_f32_32x32x16_bf16 v[0:15], v[162:165], v[192:195], v[0:15]
	v_mfma_f32_32x32x16_bf16 v[16:31], v[162:165], v[196:199], v[16:31]
	ds_read_b128 v[48:51], v144 offset:24576
	ds_read_b128 v[52:55], v145 offset:24576
	ds_read_b128 v[56:59], v144 offset:28672
	ds_read_b128 v[60:63], v145 offset:28672
	v_exp_f32_e32 v96, v96
	v_exp_f32_e32 v97, v97
	v_exp_f32_e32 v98, v98
	v_exp_f32_e32 v99, v99
	v_exp_f32_e32 v100, v100
	v_exp_f32_e32 v101, v101
	v_exp_f32_e32 v102, v102
	v_exp_f32_e32 v103, v103
	v_cvt_pk_bf16_f32 v162, v96, v97
	v_cvt_pk_bf16_f32 v163, v98, v99
	v_cvt_pk_bf16_f32 v164, v100, v101
	v_cvt_pk_bf16_f32 v165, v102, v103
	v_pk_add_f32 v[130:131], v[130:131], v[96:97]
	v_pk_add_f32 v[130:131], v[130:131], v[98:99]
	v_pk_add_f32 v[130:131], v[130:131], v[100:101]
	v_pk_add_f32 v[130:131], v[130:131], v[102:103]
	v_mfma_f32_32x32x16_bf16 v[80:95], v[162:165], v[168:171], v[80:95]
	v_exp_f32_e32 v104, v104
	v_exp_f32_e32 v105, v105
	v_exp_f32_e32 v106, v106
	v_exp_f32_e32 v107, v107
	v_mfma_f32_32x32x16_bf16 v[200:215], v[162:165], v[172:175], v[200:215]
	v_exp_f32_e32 v108, v108
	v_exp_f32_e32 v109, v109
	v_exp_f32_e32 v110, v110
	v_exp_f32_e32 v111, v111
	v_cvt_pk_bf16_f32 v162, v104, v105
	v_cvt_pk_bf16_f32 v163, v106, v107
	v_cvt_pk_bf16_f32 v164, v108, v109
	v_cvt_pk_bf16_f32 v165, v110, v111
	v_pk_add_f32 v[130:131], v[130:131], v[104:105]
	v_pk_add_f32 v[130:131], v[130:131], v[106:107]
	v_pk_add_f32 v[130:131], v[130:131], v[108:109]
	v_pk_add_f32 v[130:131], v[130:131], v[110:111]
	v_mfma_f32_32x32x16_bf16 v[80:95], v[162:165], v[176:179], v[80:95]
	v_exp_f32_e32 v112, v112
	v_exp_f32_e32 v113, v113
	v_exp_f32_e32 v114, v114
	v_exp_f32_e32 v115, v115
	v_mfma_f32_32x32x16_bf16 v[200:215], v[162:165], v[180:183], v[200:215]
	v_exp_f32_e32 v116, v116
	v_exp_f32_e32 v117, v117
	v_exp_f32_e32 v118, v118
	v_exp_f32_e32 v119, v119
	v_cvt_pk_bf16_f32 v162, v112, v113
	v_cvt_pk_bf16_f32 v163, v114, v115
	v_cvt_pk_bf16_f32 v164, v116, v117
	v_cvt_pk_bf16_f32 v165, v118, v119
	v_pk_add_f32 v[130:131], v[130:131], v[112:113]
	v_pk_add_f32 v[130:131], v[130:131], v[114:115]
	v_pk_add_f32 v[130:131], v[130:131], v[116:117]
	v_pk_add_f32 v[130:131], v[130:131], v[118:119]
	v_mfma_f32_32x32x16_bf16 v[80:95], v[162:165], v[184:187], v[80:95]
	v_exp_f32_e32 v120, v120
	v_exp_f32_e32 v121, v121
	v_exp_f32_e32 v122, v122
	v_exp_f32_e32 v123, v123
	v_mfma_f32_32x32x16_bf16 v[200:215], v[162:165], v[188:191], v[200:215]
	v_exp_f32_e32 v124, v124
	v_exp_f32_e32 v125, v125
	v_exp_f32_e32 v126, v126
	v_exp_f32_e32 v127, v127
	v_cvt_pk_bf16_f32 v162, v120, v121
	v_cvt_pk_bf16_f32 v163, v122, v123
	v_cvt_pk_bf16_f32 v164, v124, v125
	v_cvt_pk_bf16_f32 v165, v126, v127
	v_pk_add_f32 v[130:131], v[130:131], v[120:121]
	v_pk_add_f32 v[130:131], v[130:131], v[122:123]
	v_pk_add_f32 v[130:131], v[130:131], v[124:125]
	v_pk_add_f32 v[130:131], v[130:131], v[126:127]
	v_mfma_f32_32x32x16_bf16 v[80:95], v[162:165], v[192:195], v[80:95]
	v_mfma_f32_32x32x16_bf16 v[200:215], v[162:165], v[196:199], v[200:215]
	s_waitcnt lgkmcnt(0)
	v_mfma_f32_32x32x16_bf16 v[96:111], v[48:51], v[136:139], v[32:47]
	ds_read_b64_tr_b16 v[168:169], v146 offset:24576
	ds_read_b64_tr_b16 v[170:171], v146 offset:25600
	ds_read_b64_tr_b16 v[172:173], v146 offset:25088
	ds_read_b64_tr_b16 v[174:175], v146 offset:26112
	v_mfma_f32_32x32x16_bf16 v[96:111], v[52:55], v[140:143], v[96:111]
	ds_read_b64_tr_b16 v[176:177], v146 offset:26624
	ds_read_b64_tr_b16 v[178:179], v146 offset:27648
	ds_read_b64_tr_b16 v[180:181], v146 offset:27136
	ds_read_b64_tr_b16 v[182:183], v146 offset:28160
	v_mfma_f32_32x32x16_bf16 v[112:127], v[56:59], v[136:139], v[32:47]
	ds_read_b64_tr_b16 v[184:185], v146 offset:28672
	ds_read_b64_tr_b16 v[186:187], v146 offset:29696
	ds_read_b64_tr_b16 v[188:189], v146 offset:29184
	ds_read_b64_tr_b16 v[190:191], v146 offset:30208
	v_mfma_f32_32x32x16_bf16 v[112:127], v[60:63], v[140:143], v[112:127]
	ds_read_b64_tr_b16 v[192:193], v146 offset:30720
	ds_read_b64_tr_b16 v[194:195], v146 offset:31744
	ds_read_b64_tr_b16 v[196:197], v146 offset:31232
	ds_read_b64_tr_b16 v[198:199], v146 offset:32256
	v_exp_f32_e32 v96, v96
	v_exp_f32_e32 v97, v97
	v_exp_f32_e32 v98, v98
	v_exp_f32_e32 v99, v99
	v_exp_f32_e32 v100, v100
	v_exp_f32_e32 v101, v101
	v_exp_f32_e32 v102, v102
	v_exp_f32_e32 v103, v103
	v_cvt_pk_bf16_f32 v162, v96, v97
	v_cvt_pk_bf16_f32 v163, v98, v99
	v_cvt_pk_bf16_f32 v164, v100, v101
	v_cvt_pk_bf16_f32 v165, v102, v103
	v_pk_add_f32 v[128:129], v[128:129], v[96:97]
	v_pk_add_f32 v[128:129], v[128:129], v[98:99]
	v_pk_add_f32 v[128:129], v[128:129], v[100:101]
	v_pk_add_f32 v[128:129], v[128:129], v[102:103]
	s_waitcnt lgkmcnt(12)
	v_mfma_f32_32x32x16_bf16 v[0:15], v[162:165], v[168:171], v[0:15]
	v_exp_f32_e32 v104, v104
	v_exp_f32_e32 v105, v105
	v_exp_f32_e32 v106, v106
	v_exp_f32_e32 v107, v107
	v_mfma_f32_32x32x16_bf16 v[16:31], v[162:165], v[172:175], v[16:31]
	v_exp_f32_e32 v108, v108
	v_exp_f32_e32 v109, v109
	v_exp_f32_e32 v110, v110
	v_exp_f32_e32 v111, v111
	v_cvt_pk_bf16_f32 v162, v104, v105
	v_cvt_pk_bf16_f32 v163, v106, v107
	v_cvt_pk_bf16_f32 v164, v108, v109
	v_cvt_pk_bf16_f32 v165, v110, v111
	v_pk_add_f32 v[128:129], v[128:129], v[104:105]
	v_pk_add_f32 v[128:129], v[128:129], v[106:107]
	v_pk_add_f32 v[128:129], v[128:129], v[108:109]
	v_pk_add_f32 v[128:129], v[128:129], v[110:111]
	s_waitcnt lgkmcnt(8)
	v_mfma_f32_32x32x16_bf16 v[0:15], v[162:165], v[176:179], v[0:15]
	v_exp_f32_e32 v112, v112
	v_exp_f32_e32 v113, v113
	v_exp_f32_e32 v114, v114
	v_exp_f32_e32 v115, v115
	v_mfma_f32_32x32x16_bf16 v[16:31], v[162:165], v[180:183], v[16:31]
	v_mfma_f32_32x32x16_bf16 v[96:111], v[48:51], v[150:153], v[64:79]
	v_exp_f32_e32 v116, v116
	v_exp_f32_e32 v117, v117
	v_exp_f32_e32 v118, v118
	v_exp_f32_e32 v119, v119
	v_mfma_f32_32x32x16_bf16 v[96:111], v[52:55], v[154:157], v[96:111]
	v_cvt_pk_bf16_f32 v162, v112, v113
	v_cvt_pk_bf16_f32 v163, v114, v115
	v_cvt_pk_bf16_f32 v164, v116, v117
	v_cvt_pk_bf16_f32 v165, v118, v119
	v_pk_add_f32 v[128:129], v[128:129], v[112:113]
	v_pk_add_f32 v[128:129], v[128:129], v[114:115]
	v_pk_add_f32 v[128:129], v[128:129], v[116:117]
	v_pk_add_f32 v[128:129], v[128:129], v[118:119]
	s_waitcnt lgkmcnt(4)
	v_mfma_f32_32x32x16_bf16 v[0:15], v[162:165], v[184:187], v[0:15]
	v_exp_f32_e32 v120, v120
	v_exp_f32_e32 v121, v121
	v_exp_f32_e32 v122, v122
	v_exp_f32_e32 v123, v123
	v_mfma_f32_32x32x16_bf16 v[16:31], v[162:165], v[188:191], v[16:31]
	v_exp_f32_e32 v124, v124
	v_exp_f32_e32 v125, v125
	v_exp_f32_e32 v126, v126
	v_exp_f32_e32 v127, v127
	v_cvt_pk_bf16_f32 v162, v120, v121
	v_cvt_pk_bf16_f32 v163, v122, v123
	v_cvt_pk_bf16_f32 v164, v124, v125
	v_cvt_pk_bf16_f32 v165, v126, v127
	v_pk_add_f32 v[128:129], v[128:129], v[120:121]
	v_pk_add_f32 v[128:129], v[128:129], v[122:123]
	v_pk_add_f32 v[128:129], v[128:129], v[124:125]
	v_pk_add_f32 v[128:129], v[128:129], v[126:127]
	v_mfma_f32_32x32x16_bf16 v[112:127], v[56:59], v[150:153], v[64:79]
	v_mfma_f32_32x32x16_bf16 v[112:127], v[60:63], v[154:157], v[112:127]
	s_waitcnt lgkmcnt(0)
	v_mfma_f32_32x32x16_bf16 v[0:15], v[162:165], v[192:195], v[0:15]
	v_mfma_f32_32x32x16_bf16 v[16:31], v[162:165], v[196:199], v[16:31]
	v_exp_f32_e32 v96, v96
	v_exp_f32_e32 v97, v97
	v_exp_f32_e32 v98, v98
	v_exp_f32_e32 v99, v99
	v_exp_f32_e32 v100, v100
	v_exp_f32_e32 v101, v101
	v_exp_f32_e32 v102, v102
	v_exp_f32_e32 v103, v103
	v_cvt_pk_bf16_f32 v162, v96, v97
	v_cvt_pk_bf16_f32 v163, v98, v99
	v_cvt_pk_bf16_f32 v164, v100, v101
	v_cvt_pk_bf16_f32 v165, v102, v103
	v_pk_add_f32 v[130:131], v[130:131], v[96:97]
	v_pk_add_f32 v[130:131], v[130:131], v[98:99]
	v_pk_add_f32 v[130:131], v[130:131], v[100:101]
	v_pk_add_f32 v[130:131], v[130:131], v[102:103]
	v_mfma_f32_32x32x16_bf16 v[80:95], v[162:165], v[168:171], v[80:95]
	v_exp_f32_e32 v104, v104
	v_exp_f32_e32 v105, v105
	v_exp_f32_e32 v106, v106
	v_exp_f32_e32 v107, v107
	v_mfma_f32_32x32x16_bf16 v[200:215], v[162:165], v[172:175], v[200:215]
	v_exp_f32_e32 v108, v108
	v_exp_f32_e32 v109, v109
	v_exp_f32_e32 v110, v110
	v_exp_f32_e32 v111, v111
	v_cvt_pk_bf16_f32 v162, v104, v105
	v_cvt_pk_bf16_f32 v163, v106, v107
	v_cvt_pk_bf16_f32 v164, v108, v109
	v_cvt_pk_bf16_f32 v165, v110, v111
	v_pk_add_f32 v[130:131], v[130:131], v[104:105]
	v_pk_add_f32 v[130:131], v[130:131], v[106:107]
	v_pk_add_f32 v[130:131], v[130:131], v[108:109]
	v_pk_add_f32 v[130:131], v[130:131], v[110:111]
	v_mfma_f32_32x32x16_bf16 v[80:95], v[162:165], v[176:179], v[80:95]
	v_exp_f32_e32 v112, v112
	v_exp_f32_e32 v113, v113
	v_exp_f32_e32 v114, v114
	v_exp_f32_e32 v115, v115
	v_mfma_f32_32x32x16_bf16 v[200:215], v[162:165], v[180:183], v[200:215]
	v_exp_f32_e32 v116, v116
	v_exp_f32_e32 v117, v117
	v_exp_f32_e32 v118, v118
	v_exp_f32_e32 v119, v119
	v_cvt_pk_bf16_f32 v162, v112, v113
	v_cvt_pk_bf16_f32 v163, v114, v115
	v_cvt_pk_bf16_f32 v164, v116, v117
	v_cvt_pk_bf16_f32 v165, v118, v119
	v_pk_add_f32 v[130:131], v[130:131], v[112:113]
	v_pk_add_f32 v[130:131], v[130:131], v[114:115]
	v_pk_add_f32 v[130:131], v[130:131], v[116:117]
	v_pk_add_f32 v[130:131], v[130:131], v[118:119]
	v_mfma_f32_32x32x16_bf16 v[80:95], v[162:165], v[184:187], v[80:95]
	v_exp_f32_e32 v120, v120
	v_exp_f32_e32 v121, v121
	v_exp_f32_e32 v122, v122
	v_exp_f32_e32 v123, v123
	v_mfma_f32_32x32x16_bf16 v[200:215], v[162:165], v[188:191], v[200:215]
	v_exp_f32_e32 v124, v124
	v_exp_f32_e32 v125, v125
	v_exp_f32_e32 v126, v126
	v_exp_f32_e32 v127, v127
	v_cvt_pk_bf16_f32 v162, v120, v121
	v_cvt_pk_bf16_f32 v163, v122, v123
	v_cvt_pk_bf16_f32 v164, v124, v125
	v_cvt_pk_bf16_f32 v165, v126, v127
	v_pk_add_f32 v[130:131], v[130:131], v[120:121]
	v_pk_add_f32 v[130:131], v[130:131], v[122:123]
	v_pk_add_f32 v[130:131], v[130:131], v[124:125]
	v_pk_add_f32 v[130:131], v[130:131], v[126:127]
	s_cmp_eq_u32 s33, 21
	s_cbranch_scc1 .Lat_w0F3
	s_waitcnt vmcnt(4)
	s_branch .Lat_wdF3

; #define AT_LOAD(K0, K1, V0, V1, T) do { const size_t e_ = (size_t)(128 * (T) + sr) * 64 + sc; \
;         K0 = *(const bf16x8*)(kcp + e_); V0 = *(const bf16x8*)(vcp + e_); K1 = *(const bf16x8*)(kcp + e_ + 64 * 64); V1 = *(const bf16x8*)(vcp + e_ + 64 * 64); } while (0)
; #define AT_STORE(K0, K1, V0, V1, BUF) do { *(LAS bf16x8*)(lds + AT_K + (BUF) * AT_KB + kst0) = K0; *(LAS bf16x8*)(lds + AT_K + (BUF) * AT_KB + kst1) = K1; \
;         *(LAS bf16x8*)(lds + AT_V + (BUF) * AT_VB + vst0) = V0; *(LAS bf16x8*)(lds + AT_V + (BUF) * AT_VB + vst1) = V1; } while (0)
; template <int VAR>
; __device__ __forceinline__ void attn_unit(const Args& a, int l, int b, int h, int qrow0  , bool ctxu, const bf16* Z, bf16* Y, LAS unsigned char* lds) {
;     ...
;     for (int t = 0; t < NT; t += 2) {
;         __syncthreads();
;         if (t + 2 < NT) AT_LOAD(ka0, ka1, va0, va1, t + 2);
;         attn_tile(Kb0, vb0, q0, q1, negm, m, o0, o1, lacc, t == 0, wsf, r32, hi);
;         AT_STORE(kb0, kb1, vb0_, vb1_, 1);
;         __syncthreads();
;         if (t + 3 < NT) AT_LOAD(kb0, kb1, vb0_, vb1_, t + 3);
;         attn_tile(Kb0 + AT_KB, vb0 + AT_VB, q0, q1, negm, m, o0, o1, lacc, false, wsf, r32, hi);
;         if (t + 2 < NT) AT_STORE(ka0, ka1, va0, va1, 0);
.Lat_wdF3:
	s_waitcnt lgkmcnt(0)
	s_barrier
	s_cmp_eq_u32 s33, 21
	s_cbranch_scc1 .Lat_ndF3
	s_cmp_eq_u32 s8, 0
	s_cbranch_scc0 .Lat_ndF3
	s_add_u32 m0, s51, 0x4000
	s_nop 0
	global_load_lds_dwordx4 v158, s[36:37]
	s_add_u32 m0, s51, 0x6000
	s_nop 0
	global_load_lds_dwordx4 v159, s[36:37]
	s_add_u32 m0, s51, 0x10000
	s_nop 0
	global_load_lds_dwordx4 v160, s[48:49]
	s_add_u32 m0, s51, 0x12000
	s_nop 0
	global_load_lds_dwordx4 v161, s[48:49]
	s_add_u32 s36, s36, 0x4000
	s_addc_u32 s37, s37, 0
	s_add_u32 s48, s48, 0x4000
	s_addc_u32 s49, s49, 0
.Lat_ndF3:
	ds_read_b128 v[48:51], v144 offset:32768
	ds_read_b128 v[52:55], v145 offset:32768
	ds_read_b128 v[56:59], v144 offset:36864
	ds_read_b128 v[60:63], v145 offset:36864
	v_mfma_f32_32x32x16_bf16 v[80:95], v[162:165], v[192:195], v[80:95]
	v_mfma_f32_32x32x16_bf16 v[200:215], v[162:165], v[196:199], v[200:215]
	s_cmp_eq_u32 s33, 21
	s_cbranch_scc1 .Lat_nlF3
	s_cmp_eq_u32 s8, 1
	s_cbranch_scc0 .Lat_nlF3
	s_add_u32 m0, s51, 0x4000
	s_nop 0
	global_load_lds_dwordx4 v158, s[36:37]
	s_add_u32 m0, s51, 0x6000
	s_nop 0
	global_load_lds_dwordx4 v159, s[36:37]
	s_add_u32 m0, s51, 0x10000
	s_nop 0
	global_load_lds_dwordx4 v160, s[48:49]
	s_add_u32 m0, s51, 0x12000
	s_nop 0
	global_load_lds_dwordx4 v161, s[48:49]
	s_add_u32 s36, s36, 0x4000
	s_addc_u32 s37, s37, 0
	s_add_u32 s48, s48, 0x4000
	s_addc_u32 s49, s49, 0
.Lat_nlF3:
	s_waitcnt lgkmcnt(0)
	v_mfma_f32_32x32x16_bf16 v[96:111], v[48:51], v[136:139], v[32:47]
	ds_read_b64_tr_b16 v[168:169], v146 offset:32768
	ds_read_b64_tr_b16 v[170:171], v146 offset:33792
	ds_read_b64_tr_b16 v[172:173], v146 offset:33280
	ds_read_b64_tr_b16 v[174:175], v146 offset:34304
	v_mfma_f32_32x32x16_bf16 v[96:111], v[52:55], v[140:143], v[96:111]
	ds_read_b64_tr_b16 v[176:177], v146 offset:34816
	ds_read_b64_tr_b16 v[178:179], v146 offset:35840
	ds_read_b64_tr_b16 v[180:181], v146 offset:35328
	ds_read_b64_tr_b16 v[182:183], v146 offset:36352
	v_mfma_f32_32x32x16_bf16 v[112:127], v[56:59], v[136:139], v[32:47]
	ds_read_b64_tr_b16 v[184:185], v146 offset:36864
	ds_read_b64_tr_b16 v[186:187], v146 offset:37888
	ds_read_b64_tr_b16 v[188:189], v146 offset:37376
	ds_read_b64_tr_b16 v[190:191], v146 offset:38400
	v_mfma_f32_32x32x16_bf16 v[112:127], v[60:63], v[140:143], v[112:127]
	ds_read_b64_tr_b16 v[192:193], v146 offset:38912
	ds_read_b64_tr_b16 v[194:195], v146 offset:39936
	ds_read_b64_tr_b16 v[196:197], v146 offset:39424
	ds_read_b64_tr_b16 v[198:199], v146 offset:40448
	v_exp_f32_e32 v96, v96
	v_exp_f32_e32 v97, v97
	v_exp_f32_e32 v98, v98
	v_exp_f32_e32 v99, v99
	v_exp_f32_e32 v100, v100
	v_exp_f32_e32 v101, v101
	v_exp_f32_e32 v102, v102
	v_exp_f32_e32 v103, v103
	v_cvt_pk_bf16_f32 v162, v96, v97
	v_cvt_pk_bf16_f32 v163, v98, v99
	v_cvt_pk_bf16_f32 v164, v100, v101
	v_cvt_pk_bf16_f32 v165, v102, v103
	v_pk_add_f32 v[128:129], v[128:129], v[96:97]
	v_pk_add_f32 v[128:129], v[128:129], v[98:99]
	v_pk_add_f32 v[128:129], v[128:129], v[100:101]
	v_pk_add_f32 v[128:129], v[128:129], v[102:103]
	s_waitcnt lgkmcnt(12)
	v_mfma_f32_32x32x16_bf16 v[0:15], v[162:165], v[168:171], v[0:15]
	v_exp_f32_e32 v104, v104
	v_exp_f32_e32 v105, v105
	v_exp_f32_e32 v106, v106
	v_exp_f32_e32 v107, v107
	v_mfma_f32_32x32x16_bf16 v[16:31], v[162:165], v[172:175], v[16:31]
	v_exp_f32_e32 v108, v108
	v_exp_f32_e32 v109, v109
	v_exp_f32_e32 v110, v110
	v_exp_f32_e32 v111, v111
	v_cvt_pk_bf16_f32 v162, v104, v105
	v_cvt_pk_bf16_f32 v163, v106, v107
	v_cvt_pk_bf16_f32 v164, v108, v109
	v_cvt_pk_bf16_f32 v165, v110, v111
	v_pk_add_f32 v[128:129], v[128:129], v[104:105]
	v_pk_add_f32 v[128:129], v[128:129], v[106:107]
	v_pk_add_f32 v[128:129], v[128:129], v[108:109]
	v_pk_add_f32 v[128:129], v[128:129], v[110:111]
	s_waitcnt lgkmcnt(8)
	v_mfma_f32_32x32x16_bf16 v[0:15], v[162:165], v[176:179], v[0:15]
	v_exp_f32_e32 v112, v112
	v_exp_f32_e32 v113, v113
	v_exp_f32_e32 v114, v114
	v_exp_f32_e32 v115, v115
	v_mfma_f32_32x32x16_bf16 v[16:31], v[162:165], v[180:183], v[16:31]
	v_mfma_f32_32x32x16_bf16 v[96:111], v[48:51], v[150:153], v[64:79]
	v_exp_f32_e32 v116, v116
	v_exp_f32_e32 v117, v117
	v_exp_f32_e32 v118, v118
	v_exp_f32_e32 v119, v119
	v_mfma_f32_32x32x16_bf16 v[96:111], v[52:55], v[154:157], v[96:111]
	v_cvt_pk_bf16_f32 v162, v112, v113
	v_cvt_pk_bf16_f32 v163, v114, v115
	v_cvt_pk_bf16_f32 v164, v116, v117
	v_cvt_pk_bf16_f32 v165, v118, v119
	v_pk_add_f32 v[128:129], v[128:129], v[112:113]
	v_pk_add_f32 v[128:129], v[128:129], v[114:115]
	v_pk_add_f32 v[128:129], v[128:129], v[116:117]
	v_pk_add_f32 v[128:129], v[128:129], v[118:119]
	s_waitcnt lgkmcnt(4)
	v_mfma_f32_32x32x16_bf16 v[0:15], v[162:165], v[184:187], v[0:15]
	v_exp_f32_e32 v120, v120
	v_exp_f32_e32 v121, v121
	v_exp_f32_e32 v122, v122
	v_exp_f32_e32 v123, v123
	v_mfma_f32_32x32x16_bf16 v[16:31], v[162:165], v[188:191], v[16:31]
	v_exp_f32_e32 v124, v124
	v_exp_f32_e32 v125, v125
	v_exp_f32_e32 v126, v126
	v_exp_f32_e32 v127, v127
	v_cvt_pk_bf16_f32 v162, v120, v121
	v_cvt_pk_bf16_f32 v163, v122, v123
	v_cvt_pk_bf16_f32 v164, v124, v125
	v_cvt_pk_bf16_f32 v165, v126, v127
	v_pk_add_f32 v[128:129], v[128:129], v[120:121]
	v_pk_add_f32 v[128:129], v[128:129], v[122:123]
	v_pk_add_f32 v[128:129], v[128:129], v[124:125]
	v_pk_add_f32 v[128:129], v[128:129], v[126:127]
	v_mfma_f32_32x32x16_bf16 v[112:127], v[56:59], v[150:153], v[64:79]
	v_mfma_f32_32x32x16_bf16 v[112:127], v[60:63], v[154:157], v[112:127]
	s_waitcnt lgkmcnt(0)
	v_mfma_f32_32x32x16_bf16 v[0:15], v[162:165], v[192:195], v[0:15]
	v_mfma_f32_32x32x16_bf16 v[16:31], v[162:165], v[196:199], v[16:31]
	ds_read_b128 v[48:51], v144 offset:40960
	ds_read_b128 v[52:55], v145 offset:40960
	ds_read_b128 v[56:59], v144 offset:45056
	ds_read_b128 v[60:63], v145 offset:45056
	v_exp_f32_e32 v96, v96
	v_exp_f32_e32 v97, v97
	v_exp_f32_e32 v98, v98
	v_exp_f32_e32 v99, v99
	v_exp_f32_e32 v100, v100
	v_exp_f32_e32 v101, v101
	v_exp_f32_e32 v102, v102
	v_exp_f32_e32 v103, v103
	v_cvt_pk_bf16_f32 v162, v96, v97
	v_cvt_pk_bf16_f32 v163, v98, v99
	v_cvt_pk_bf16_f32 v164, v100, v101
	v_cvt_pk_bf16_f32 v165, v102, v103
	v_pk_add_f32 v[130:131], v[130:131], v[96:97]
	v_pk_add_f32 v[130:131], v[130:131], v[98:99]
	v_pk_add_f32 v[130:131], v[130:131], v[100:101]
	v_pk_add_f32 v[130:131], v[130:131], v[102:103]
	v_mfma_f32_32x32x16_bf16 v[80:95], v[162:165], v[168:171], v[80:95]
	v_exp_f32_e32 v104, v104
	v_exp_f32_e32 v105, v105
	v_exp_f32_e32 v106, v106
	v_exp_f32_e32 v107, v107
	v_mfma_f32_32x32x16_bf16 v[200:215], v[162:165], v[172:175], v[200:215]
	v_exp_f32_e32 v108, v108
	v_exp_f32_e32 v109, v109
	v_exp_f32_e32 v110, v110
	v_exp_f32_e32 v111, v111
	v_cvt_pk_bf16_f32 v162, v104, v105
	v_cvt_pk_bf16_f32 v163, v106, v107
	v_cvt_pk_bf16_f32 v164, v108, v109
	v_cvt_pk_bf16_f32 v165, v110, v111
	v_pk_add_f32 v[130:131], v[130:131], v[104:105]
	v_pk_add_f32 v[130:131], v[130:131], v[106:107]
	v_pk_add_f32 v[130:131], v[130:131], v[108:109]
	v_pk_add_f32 v[130:131], v[130:131], v[110:111]
	v_mfma_f32_32x32x16_bf16 v[80:95], v[162:165], v[176:179], v[80:95]
	v_exp_f32_e32 v112, v112
	v_exp_f32_e32 v113, v113
	v_exp_f32_e32 v114, v114
	v_exp_f32_e32 v115, v115
	v_mfma_f32_32x32x16_bf16 v[200:215], v[162:165], v[180:183], v[200:215]
	v_exp_f32_e32 v116, v116
	v_exp_f32_e32 v117, v117
	v_exp_f32_e32 v118, v118
	v_exp_f32_e32 v119, v119
	v_cvt_pk_bf16_f32 v162, v112, v113
	v_cvt_pk_bf16_f32 v163, v114, v115
	v_cvt_pk_bf16_f32 v164, v116, v117
	v_cvt_pk_bf16_f32 v165, v118, v119
	v_pk_add_f32 v[130:131], v[130:131], v[112:113]
	v_pk_add_f32 v[130:131], v[130:131], v[114:115]
	v_pk_add_f32 v[130:131], v[130:131], v[116:117]
	v_pk_add_f32 v[130:131], v[130:131], v[118:119]
	v_mfma_f32_32x32x16_bf16 v[80:95], v[162:165], v[184:187], v[80:95]
	v_exp_f32_e32 v120, v120
	v_exp_f32_e32 v121, v121
	v_exp_f32_e32 v122, v122
	v_exp_f32_e32 v123, v123
	v_mfma_f32_32x32x16_bf16 v[200:215], v[162:165], v[188:191], v[200:215]
	v_exp_f32_e32 v124, v124
	v_exp_f32_e32 v125, v125
	v_exp_f32_e32 v126, v126
	v_exp_f32_e32 v127, v127
	v_cvt_pk_bf16_f32 v162, v120, v121
	v_cvt_pk_bf16_f32 v163, v122, v123
	v_cvt_pk_bf16_f32 v164, v124, v125
	v_cvt_pk_bf16_f32 v165, v126, v127
	v_pk_add_f32 v[130:131], v[130:131], v[120:121]
	v_pk_add_f32 v[130:131], v[130:131], v[122:123]
	v_pk_add_f32 v[130:131], v[130:131], v[124:125]
	v_pk_add_f32 v[130:131], v[130:131], v[126:127]
	v_mfma_f32_32x32x16_bf16 v[80:95], v[162:165], v[192:195], v[80:95]
	v_mfma_f32_32x32x16_bf16 v[200:215], v[162:165], v[196:199], v[200:215]
	s_waitcnt lgkmcnt(0)
	v_mfma_f32_32x32x16_bf16 v[96:111], v[48:51], v[136:139], v[32:47]
	ds_read_b64_tr_b16 v[168:169], v146 offset:40960
	ds_read_b64_tr_b16 v[170:171], v146 offset:41984
	ds_read_b64_tr_b16 v[172:173], v146 offset:41472
	ds_read_b64_tr_b16 v[174:175], v146 offset:42496
	v_mfma_f32_32x32x16_bf16 v[96:111], v[52:55], v[140:143], v[96:111]
	ds_read_b64_tr_b16 v[176:177], v146 offset:43008
	ds_read_b64_tr_b16 v[178:179], v146 offset:44032
	ds_read_b64_tr_b16 v[180:181], v146 offset:43520
	ds_read_b64_tr_b16 v[182:183], v146 offset:44544
	v_mfma_f32_32x32x16_bf16 v[112:127], v[56:59], v[136:139], v[32:47]
	ds_read_b64_tr_b16 v[184:185], v146 offset:45056
	ds_read_b64_tr_b16 v[186:187], v146 offset:46080
	ds_read_b64_tr_b16 v[188:189], v146 offset:45568
	ds_read_b64_tr_b16 v[190:191], v146 offset:46592
	v_mfma_f32_32x32x16_bf16 v[112:127], v[60:63], v[140:143], v[112:127]
	ds_read_b64_tr_b16 v[192:193], v146 offset:47104
	ds_read_b64_tr_b16 v[194:195], v146 offset:48128
	ds_read_b64_tr_b16 v[196:197], v146 offset:47616
	ds_read_b64_tr_b16 v[198:199], v146 offset:48640
	v_exp_f32_e32 v96, v96
	v_exp_f32_e32 v97, v97
	v_exp_f32_e32 v98, v98
	v_exp_f32_e32 v99, v99
	v_exp_f32_e32 v100, v100
	v_exp_f32_e32 v101, v101
	v_exp_f32_e32 v102, v102
	v_exp_f32_e32 v103, v103
	v_cvt_pk_bf16_f32 v162, v96, v97
	v_cvt_pk_bf16_f32 v163, v98, v99
	v_cvt_pk_bf16_f32 v164, v100, v101
	v_cvt_pk_bf16_f32 v165, v102, v103
	v_pk_add_f32 v[128:129], v[128:129], v[96:97]
	v_pk_add_f32 v[128:129], v[128:129], v[98:99]
	v_pk_add_f32 v[128:129], v[128:129], v[100:101]
	v_pk_add_f32 v[128:129], v[128:129], v[102:103]
	s_waitcnt lgkmcnt(12)
	v_mfma_f32_32x32x16_bf16 v[0:15], v[162:165], v[168:171], v[0:15]
	v_exp_f32_e32 v104, v104
	v_exp_f32_e32 v105, v105
	v_exp_f32_e32 v106, v106
	v_exp_f32_e32 v107, v107
	v_mfma_f32_32x32x16_bf16 v[16:31], v[162:165], v[172:175], v[16:31]
	v_exp_f32_e32 v108, v108
	v_exp_f32_e32 v109, v109
	v_exp_f32_e32 v110, v110
	v_exp_f32_e32 v111, v111
	v_cvt_pk_bf16_f32 v162, v104, v105
	v_cvt_pk_bf16_f32 v163, v106, v107
	v_cvt_pk_bf16_f32 v164, v108, v109
	v_cvt_pk_bf16_f32 v165, v110, v111
	v_pk_add_f32 v[128:129], v[128:129], v[104:105]
	v_pk_add_f32 v[128:129], v[128:129], v[106:107]
	v_pk_add_f32 v[128:129], v[128:129], v[108:109]
	v_pk_add_f32 v[128:129], v[128:129], v[110:111]
	s_waitcnt lgkmcnt(8)
	v_mfma_f32_32x32x16_bf16 v[0:15], v[162:165], v[176:179], v[0:15]
	v_exp_f32_e32 v112, v112
	v_exp_f32_e32 v113, v113
	v_exp_f32_e32 v114, v114
	v_exp_f32_e32 v115, v115
	v_mfma_f32_32x32x16_bf16 v[16:31], v[162:165], v[180:183], v[16:31]
	v_mfma_f32_32x32x16_bf16 v[96:111], v[48:51], v[150:153], v[64:79]
	v_exp_f32_e32 v116, v116
	v_exp_f32_e32 v117, v117
	v_exp_f32_e32 v118, v118
	v_exp_f32_e32 v119, v119
	v_mfma_f32_32x32x16_bf16 v[96:111], v[52:55], v[154:157], v[96:111]
	v_cvt_pk_bf16_f32 v162, v112, v113
	v_cvt_pk_bf16_f32 v163, v114, v115
	v_cvt_pk_bf16_f32 v164, v116, v117
	v_cvt_pk_bf16_f32 v165, v118, v119
	v_pk_add_f32 v[128:129], v[128:129], v[112:113]
	v_pk_add_f32 v[128:129], v[128:129], v[114:115]
	v_pk_add_f32 v[128:129], v[128:129], v[116:117]
	v_pk_add_f32 v[128:129], v[128:129], v[118:119]
	s_waitcnt lgkmcnt(4)
	v_mfma_f32_32x32x16_bf16 v[0:15], v[162:165], v[184:187], v[0:15]
	v_exp_f32_e32 v120, v120
	v_exp_f32_e32 v121, v121
	v_exp_f32_e32 v122, v122
	v_exp_f32_e32 v123, v123
	v_mfma_f32_32x32x16_bf16 v[16:31], v[162:165], v[188:191], v[16:31]
	v_exp_f32_e32 v124, v124
	v_exp_f32_e32 v125, v125
	v_exp_f32_e32 v126, v126
	v_exp_f32_e32 v127, v127
	v_cvt_pk_bf16_f32 v162, v120, v121
	v_cvt_pk_bf16_f32 v163, v122, v123
	v_cvt_pk_bf16_f32 v164, v124, v125
	v_cvt_pk_bf16_f32 v165, v126, v127
	v_pk_add_f32 v[128:129], v[128:129], v[120:121]
	v_pk_add_f32 v[128:129], v[128:129], v[122:123]
	v_pk_add_f32 v[128:129], v[128:129], v[124:125]
	v_pk_add_f32 v[128:129], v[128:129], v[126:127]
	v_mfma_f32_32x32x16_bf16 v[112:127], v[56:59], v[150:153], v[64:79]
	v_mfma_f32_32x32x16_bf16 v[112:127], v[60:63], v[154:157], v[112:127]
	s_waitcnt lgkmcnt(0)
	v_mfma_f32_32x32x16_bf16 v[0:15], v[162:165], v[192:195], v[0:15]
	v_mfma_f32_32x32x16_bf16 v[16:31], v[162:165], v[196:199], v[16:31]
	v_exp_f32_e32 v96, v96
	v_exp_f32_e32 v97, v97
	v_exp_f32_e32 v98, v98
	v_exp_f32_e32 v99, v99
	v_exp_f32_e32 v100, v100
	v_exp_f32_e32 v101, v101
	v_exp_f32_e32 v102, v102
	v_exp_f32_e32 v103, v103
	v_cvt_pk_bf16_f32 v162, v96, v97
	v_cvt_pk_bf16_f32 v163, v98, v99
	v_cvt_pk_bf16_f32 v164, v100, v101
	v_cvt_pk_bf16_f32 v165, v102, v103
	v_pk_add_f32 v[130:131], v[130:131], v[96:97]
	v_pk_add_f32 v[130:131], v[130:131], v[98:99]
	v_pk_add_f32 v[130:131], v[130:131], v[100:101]
	v_pk_add_f32 v[130:131], v[130:131], v[102:103]
	v_mfma_f32_32x32x16_bf16 v[80:95], v[162:165], v[168:171], v[80:95]
	v_exp_f32_e32 v104, v104
	v_exp_f32_e32 v105, v105
	v_exp_f32_e32 v106, v106
	v_exp_f32_e32 v107, v107
	v_mfma_f32_32x32x16_bf16 v[200:215], v[162:165], v[172:175], v[200:215]
	v_exp_f32_e32 v108, v108
	v_exp_f32_e32 v109, v109
	v_exp_f32_e32 v110, v110
	v_exp_f32_e32 v111, v111
	v_cvt_pk_bf16_f32 v162, v104, v105
	v_cvt_pk_bf16_f32 v163, v106, v107
	v_cvt_pk_bf16_f32 v164, v108, v109
	v_cvt_pk_bf16_f32 v165, v110, v111
	v_pk_add_f32 v[130:131], v[130:131], v[104:105]
	v_pk_add_f32 v[130:131], v[130:131], v[106:107]
	v_pk_add_f32 v[130:131], v[130:131], v[108:109]
	v_pk_add_f32 v[130:131], v[130:131], v[110:111]
	v_mfma_f32_32x32x16_bf16 v[80:95], v[162:165], v[176:179], v[80:95]
	v_exp_f32_e32 v112, v112
	v_exp_f32_e32 v113, v113
	v_exp_f32_e32 v114, v114
	v_exp_f32_e32 v115, v115
	v_mfma_f32_32x32x16_bf16 v[200:215], v[162:165], v[180:183], v[200:215]
	v_exp_f32_e32 v116, v116
	v_exp_f32_e32 v117, v117
	v_exp_f32_e32 v118, v118
	v_exp_f32_e32 v119, v119
	v_cvt_pk_bf16_f32 v162, v112, v113
	v_cvt_pk_bf16_f32 v163, v114, v115
	v_cvt_pk_bf16_f32 v164, v116, v117
	v_cvt_pk_bf16_f32 v165, v118, v119
	v_pk_add_f32 v[130:131], v[130:131], v[112:113]
	v_pk_add_f32 v[130:131], v[130:131], v[114:115]
	v_pk_add_f32 v[130:131], v[130:131], v[116:117]
	v_pk_add_f32 v[130:131], v[130:131], v[118:119]
	v_mfma_f32_32x32x16_bf16 v[80:95], v[162:165], v[184:187], v[80:95]
	v_exp_f32_e32 v120, v120
	v_exp_f32_e32 v121, v121
	v_exp_f32_e32 v122, v122
	v_exp_f32_e32 v123, v123
	v_mfma_f32_32x32x16_bf16 v[200:215], v[162:165], v[188:191], v[200:215]
	v_exp_f32_e32 v124, v124
	v_exp_f32_e32 v125, v125
	v_exp_f32_e32 v126, v126
	v_exp_f32_e32 v127, v127
	v_cvt_pk_bf16_f32 v162, v120, v121
	v_cvt_pk_bf16_f32 v163, v122, v123
	v_cvt_pk_bf16_f32 v164, v124, v125
	v_cvt_pk_bf16_f32 v165, v126, v127
	v_pk_add_f32 v[130:131], v[130:131], v[120:121]
	v_pk_add_f32 v[130:131], v[130:131], v[122:123]
	v_pk_add_f32 v[130:131], v[130:131], v[124:125]
	v_pk_add_f32 v[130:131], v[130:131], v[126:127]
	s_cmp_eq_u32 s33, 21
	s_cbranch_scc1 .Lat_w0F5
	s_waitcnt vmcnt(4)
	s_branch .Lat_wdF5

; #define LAS __attribute__((address_space(3)))
; __device__ __forceinline__ int crow(int r, int hi) { return (r & 3) + 8 * (r >> 2) + 4 * hi; }
; template <int VAR>
; __device__ __forceinline__ void attn_unit(const Args& a, int l, int b, int h, int qrow0  , bool ctxu, const bf16* Z, bf16* Y, LAS unsigned char* lds) {
;     ...
;     for (int t = 0; t < NT; t += 2) {
;         __syncthreads();
;         if (t + 2 < NT) AT_LOAD(ka0, ka1, va0, va1, t + 2);
;         attn_tile(Kb0, vb0, q0, q1, negm, m, o0, o1, lacc, t == 0, wsf, r32, hi);
;         AT_STORE(kb0, kb1, vb0_, vb1_, 1);
;         __syncthreads();
;         if (t + 3 < NT) AT_LOAD(kb0, kb1, vb0_, vb1_, t + 3);
;         attn_tile(Kb0 + AT_KB, vb0 + AT_VB, q0, q1, negm, m, o0, o1, lacc, false, wsf, r32, hi);
;         if (t + 2 < NT) AT_STORE(ka0, ka1, va0, va1, 0);
;     }
;     ...
;     float lam, omli;
;     { float s1 = 0.f, s2 = 0.f;
;       for (int i = 0; i < 32; ++i) { s1 += a.lam_q1[l * 32 + i] * a.lam_k1[l * 32 + i]; s2 += a.lam_q2[l * 32 + i] * a.lam_k2[l * 32 + i]; }
;       const float li = 0.8f - 0.6f * expf(-0.3f * (float)l); lam = expf(s1) - expf(s2) + li; omli = 1.f - li; }
;     LAS float* stg = (LAS float*)(lds + AT_ST) + wq * 2048;
;     if (comp == 1) {
; #pragma unroll
;         for (int r = 0; r < 16; ++r) { const int qr = crow(r, hi); const float il = lam * __builtin_amdgcn_rcpf(lacc[r]); stg[qr * 64 + r32] = o0[r] * il; stg[qr * 64 + 32 + r32] = o1[r] * il; }
;     }
;     __syncthreads();
;     if (comp == 0) {
; #pragma unroll
;         for (int r = 0; r < 16; ++r) { const int qr = crow(r, hi); const float il = __builtin_amdgcn_rcpf(lacc[r]); o0[r] = o0[r] * il - stg[qr * 64 + r32]; o1[r] = o1[r] * il - stg[qr * 64 + 32 + r32]; }
;         asm volatile("s_waitcnt lgkmcnt(0)" ::: "memory");
; #pragma unroll
;         for (int r = 0; r < 16; ++r) { const int qr = crow(r, hi); stg[qr * 64 + r32] = o0[r]; stg[qr * 64 + 32 + r32] = o1[r]; }
;         asm volatile("s_waitcnt lgkmcnt(0)" ::: "memory");
;         const int ch = lane & 7;
;         float gsub[8];
; #pragma unroll
;         for (int i = 0; i < 8; ++i) gsub[i] = a.subln_g[l * 64 + ch * 8 + i] * omli;
.Lat_wdF5:
	s_waitcnt lgkmcnt(0)
	s_barrier
	s_cmp_eq_u32 s33, 21
	s_cbranch_scc1 .Lat_ndF5
	s_cmp_eq_u32 s8, 0
	s_cbranch_scc0 .Lat_ndF5
	s_add_u32 m0, s51, 0x8000
	s_nop 0
	global_load_lds_dwordx4 v158, s[36:37]
	s_add_u32 m0, s51, 0xa000
	s_nop 0
	global_load_lds_dwordx4 v159, s[36:37]
	s_add_u32 m0, s51, 0x14000
	s_nop 0
	global_load_lds_dwordx4 v160, s[48:49]
	s_add_u32 m0, s51, 0x16000
	s_nop 0
	global_load_lds_dwordx4 v161, s[48:49]
	s_add_u32 s36, s36, 0x4000
	s_addc_u32 s37, s37, 0
	s_add_u32 s48, s48, 0x4000
	s_addc_u32 s49, s49, 0
.Lat_ndF5:
	ds_read_b128 v[48:51], v144 offset:0
	ds_read_b128 v[52:55], v145 offset:0
	ds_read_b128 v[56:59], v144 offset:4096
	ds_read_b128 v[60:63], v145 offset:4096
	v_mfma_f32_32x32x16_bf16 v[80:95], v[162:165], v[192:195], v[80:95]
	v_mfma_f32_32x32x16_bf16 v[200:215], v[162:165], v[196:199], v[200:215]
	s_cmp_eq_u32 s33, 21
	s_cbranch_scc1 .Lat_nlF5
	s_cmp_eq_u32 s8, 1
	s_cbranch_scc0 .Lat_nlF5
	s_add_u32 m0, s51, 0x8000
	s_nop 0
	global_load_lds_dwordx4 v158, s[36:37]
	s_add_u32 m0, s51, 0xa000
	s_nop 0
	global_load_lds_dwordx4 v159, s[36:37]
	s_add_u32 m0, s51, 0x14000
	s_nop 0
	global_load_lds_dwordx4 v160, s[48:49]
	s_add_u32 m0, s51, 0x16000
	s_nop 0
	global_load_lds_dwordx4 v161, s[48:49]
	s_add_u32 s36, s36, 0x4000
	s_addc_u32 s37, s37, 0
	s_add_u32 s48, s48, 0x4000
	s_addc_u32 s49, s49, 0
.Lat_nlF5:
	s_add_u32 s33, s33, 1
	s_cmp_lt_u32 s33, 22
	s_cbranch_scc1 .Lat_floop
	v_add_f32_e32 v132, v128, v129
	v_mov_b32_e32 v133, v132
	s_nop 1
	v_permlane32_swap_b32_e32 v132, v133
	v_add_f32_e32 v135, v132, v133
	v_add_f32_e32 v132, v130, v131
	v_mov_b32_e32 v133, v132
	s_nop 1
	v_permlane32_swap_b32_e32 v132, v133
	v_add_f32_e32 v130, v132, v133
	s_nop 7
	s_nop 7
	v_add_f32_e32 v132, v135, v130
	v_mov_b32_e32 v133, 0
	v_add_f32_e64 v132, v132, |v0|
	v_add_f32_e64 v133, v133, |v1|
	v_add_f32_e64 v132, v132, |v2|
	v_add_f32_e64 v133, v133, |v3|
	v_add_f32_e64 v132, v132, |v4|
	v_add_f32_e64 v133, v133, |v5|
	v_add_f32_e64 v132, v132, |v6|
	v_add_f32_e64 v133, v133, |v7|
	v_add_f32_e64 v132, v132, |v8|
	v_add_f32_e64 v133, v133, |v9|
	v_add_f32_e64 v132, v132, |v10|
	v_add_f32_e64 v133, v133, |v11|
	v_add_f32_e64 v132, v132, |v12|
	v_add_f32_e64 v133, v133, |v13|
	v_add_f32_e64 v132, v132, |v14|
	v_add_f32_e64 v133, v133, |v15|
	v_add_f32_e64 v132, v132, |v16|
	v_add_f32_e64 v133, v133, |v17|
	v_add_f32_e64 v132, v132, |v18|
	v_add_f32_e64 v133, v133, |v19|
	v_add_f32_e64 v132, v132, |v20|
	v_add_f32_e64 v133, v133, |v21|
	v_add_f32_e64 v132, v132, |v22|
	v_add_f32_e64 v133, v133, |v23|
	v_add_f32_e64 v132, v132, |v24|
	v_add_f32_e64 v133, v133, |v25|
	v_add_f32_e64 v132, v132, |v26|
	v_add_f32_e64 v133, v133, |v27|
	v_add_f32_e64 v132, v132, |v28|
	v_add_f32_e64 v133, v133, |v29|
	v_add_f32_e64 v132, v132, |v30|
	v_add_f32_e64 v133, v133, |v31|
	v_add_f32_e64 v132, v132, |v80|
	v_add_f32_e64 v133, v133, |v81|
	v_add_f32_e64 v132, v132, |v82|
	v_add_f32_e64 v133, v133, |v83|
	v_add_f32_e64 v132, v132, |v84|
	v_add_f32_e64 v133, v133, |v85|
	v_add_f32_e64 v132, v132, |v86|
	v_add_f32_e64 v133, v133, |v87|
	v_add_f32_e64 v132, v132, |v88|
	v_add_f32_e64 v133, v133, |v89|
	v_add_f32_e64 v132, v132, |v90|
	v_add_f32_e64 v133, v133, |v91|
	v_add_f32_e64 v132, v132, |v92|
	v_add_f32_e64 v133, v133, |v93|
	v_add_f32_e64 v132, v132, |v94|
	v_add_f32_e64 v133, v133, |v95|
	v_add_f32_e64 v132, v132, |v200|
	v_add_f32_e64 v133, v133, |v201|
	v_add_f32_e64 v132, v132, |v202|
	v_add_f32_e64 v133, v133, |v203|
	v_add_f32_e64 v132, v132, |v204|
	v_add_f32_e64 v133, v133, |v205|
	v_add_f32_e64 v132, v132, |v206|
	v_add_f32_e64 v133, v133, |v207|
	v_add_f32_e64 v132, v132, |v208|
	v_add_f32_e64 v133, v133, |v209|
	v_add_f32_e64 v132, v132, |v210|
	v_add_f32_e64 v133, v133, |v211|
	v_add_f32_e64 v132, v132, |v212|
	v_add_f32_e64 v133, v133, |v213|
	v_add_f32_e64 v132, v132, |v214|
	v_add_f32_e64 v133, v133, |v215|
	v_add_f32_e32 v132, v132, v133
	v_mov_b32_e32 v133, 0x76800000
	v_cmp_nlt_f32_e32 vcc, v132, v133
	s_cmp_lg_u64 vcc, 0
	s_cselect_b32 s50, 1, 0
	v_mov_b32_e32 v134, 0x19880
	v_mov_b32_e32 v133, s50
	ds_or_b32 v134, v133
	s_waitcnt lgkmcnt(0)
	s_barrier
	ds_read_b32 v133, v134
	s_waitcnt lgkmcnt(0)
	v_readfirstlane_b32 s50, v133
	s_cmp_lg_u32 s50, 0
	s_cbranch_scc1 .Lat_safe_entry
	s_nop 7
	s_waitcnt lgkmcnt(0)
	ds_write_b32 v148, v135
	s_waitcnt lgkmcnt(0)
	ds_read_b128 v[32:35], v147 offset:0
	ds_read_b128 v[36:39], v147 offset:32
	ds_read_b128 v[40:43], v147 offset:64
	ds_read_b128 v[44:47], v147 offset:96
	s_waitcnt lgkmcnt(0)
	s_mov_b32 s93, 0
	s_waitcnt vmcnt(0)
	v_or_b32_e32 v132, s58, v228
	v_mov_b32_e32 v133, 0
	v_lshl_add_u64 v[132:133], v[132:133], 2, s[78:79]
	global_load_dwordx4 v[100:103], v[132:133], off offset:16
	global_load_dwordx4 v[96:99], v[132:133], off
	s_setprio 0
	s_branch .LBB0_459
